# DIL V-loads kept in flight (vmcnt 8) + NA K-prefetch kept in flight across chunk
# baseline (speedup 1.0000x reference)
.LBB0_661:
	v_mov_b32_e32 v82, s84
	v_cndmask_b32_e64 v106, v150, v82, s[6:7]
	v_add_u32_e32 v82, v106, v146
	v_add_u32_e32 v90, s35, v82
	v_med3_i32 v83, v82, 0, v124
	v_med3_i32 v82, v90, 0, v124
	v_add_u32_e32 v90, s35, v90
	v_add_u32_e32 v91, v106, v152
	v_add_u32_e32 v98, v106, v153
	v_add_u32_e32 v99, v106, v156
	v_add_u32_e32 v107, v106, v157
	v_add_u32_e32 v106, v106, v158
	v_med3_i32 v90, v90, 0, v124
	v_med3_i32 v91, v91, 0, v124
	v_med3_i32 v98, v98, 0, v124
	v_med3_i32 v99, v99, 0, v124
	v_med3_i32 v107, v107, 0, v124
	v_med3_i32 v106, v106, 0, v124
	v_lshl_add_u32 v83, v83, 12, v147
	v_lshl_add_u32 v86, v82, 12, v147
	v_lshl_add_u32 v90, v90, 12, v147
	v_lshl_add_u32 v94, v91, 12, v147
	v_lshl_add_u32 v98, v98, 12, v148
	v_lshl_add_u32 v102, v99, 12, v148
	v_lshl_add_u32 v107, v107, 12, v148
	v_lshl_add_u32 v110, v106, 12, v149
	global_load_dwordx4 v[82:85], v83, s[54:55]
	s_nop 0
	global_load_dwordx4 v[86:89], v86, s[54:55]
	s_nop 0
	global_load_dwordx4 v[90:93], v90, s[54:55]
	s_nop 0
	global_load_dwordx4 v[94:97], v94, s[54:55]
	s_nop 0
	global_load_dwordx4 v[98:101], v98, s[54:55]
	s_nop 0
	global_load_dwordx4 v[102:105], v102, s[54:55]
	s_nop 0
	global_load_dwordx4 v[106:109], v107, s[54:55]
	s_nop 0
	global_load_dwordx4 v[110:113], v110, s[54:55]
	v_add_u32_e32 v114, v173, v177
	s_waitcnt vmcnt(8)
	ds_write_b128 v114, v[2:5]
	ds_write_b128 v114, v[18:21] offset:8704
	ds_write_b128 v114, v[6:9] offset:17408
	ds_write_b128 v114, v[22:25] offset:26112
	ds_write_b128 v114, v[10:13] offset:34816
	ds_write_b128 v114, v[26:29] offset:43520
	ds_write_b128 v114, v[14:17] offset:52224
	ds_write_b128 v114, v[30:33] offset:60928
	s_and_saveexec_b64 s[26:27], s[0:1]
	s_cbranch_execz .LBB0_663
	v_pk_add_f32 v[196:197], v[120:121], v[118:119]
	s_nop 0
	v_add_f32_e32 v114, v196, v197
	v_fmamk_f32 v114, v114, 0x3c000000, v141
	v_rsq_f32_e32 v114, v114
	ds_write_b32 v176, v114

.LBB0_670:
	s_or_b64 s[26:27], s[76:77], s[26:27]
	s_mov_b64 s[98:99], s[26:27]
	s_andn2_b64 vcc, exec, s[26:27]
	s_cbranch_vccnz .LBB0_672
	v_mad_i32_i24 v6, s42, v155, v114
	s_lshl_b32 s27, s42, 5
	v_med3_i32 v2, v6, 0, v124
	v_add_u32_e32 v6, s27, v6
	v_and_b32_e32 v11, s33, v165
	s_lshl_b32 s26, s43, 24
	v_lshl_or_b32 v3, s31, 8, v164
	v_med3_i32 v7, v6, 0, v124
	v_add_u32_e32 v6, s27, v6
	v_mad_i32_i24 v11, v11, s42, v114
	v_and_b32_e32 v30, s33, v169
	v_add_u32_e32 v10, s26, v3
	v_med3_i32 v6, v6, 0, v124
	v_med3_i32 v11, v11, 0, v124
	s_add_i32 s27, s31, s30
	v_and_b32_e32 v15, s33, v167
	v_mad_i32_i24 v30, v30, s42, v114
	v_and_b32_e64 v31, s30, 1
	v_lshl_add_u32 v2, v2, 12, v10
	v_lshl_add_u32 v7, v7, 12, v10
	v_lshl_add_u32 v6, v6, 12, v10
	v_lshl_add_u32 v10, v11, 12, v10
	v_lshl_or_b32 v11, s27, 8, v164
	v_mad_i32_i24 v15, v15, s42, v114
	v_med3_i32 v30, v30, 0, v124
	v_add_u32_e32 v31, s31, v31
	v_add_u32_e32 v14, s26, v11
	v_med3_i32 v15, v15, 0, v124
	v_lshlrev_b32_e32 v30, 12, v30
	v_lshl_or_b32 v31, v31, 8, v164
	v_lshl_add_u32 v15, v15, 12, v14
	v_add3_u32 v30, v31, s26, v30
	global_load_dwordx4 v[18:21], v7, s[52:53]
	global_load_dwordx4 v[22:25], v10, s[52:53]
	v_and_b32_e32 v10, s33, v166
	global_load_dwordx4 v[26:29], v15, s[52:53]
	v_and_b32_sdwa v118, s33, v0 dst_sel:DWORD dst_unused:UNUSED_PAD src0_sel:DWORD src1_sel:BYTE_0
	global_load_dwordx4 v[30:33], v30, s[52:53]
	v_and_b32_e32 v15, s33, v168
	v_mad_i32_i24 v10, v10, s42, v114
	v_mad_i32_i24 v15, v15, s42, v114
	v_mad_i32_i24 v114, v118, s42, v114
	v_and_b32_e32 v118, s30, v170
	v_add_u32_e32 v118, s31, v118
	s_lshl_b32 s26, s43, 12
	v_med3_i32 v114, v114, 0, v124
	v_lshl_add_u32 v118, v118, 13, s26
	v_or_b32_e32 v114, v118, v114
	v_add_u32_e32 v114, 0x20000, v114
	v_lshl_add_u64 v[196:197], v[114:115], 2, s[56:57]
	v_add_co_u32_e32 v120, vcc, 0x100000, v196
	v_med3_i32 v10, v10, 0, v124
	s_nop 0
	v_addc_co_u32_e32 v121, vcc, 0, v197, vcc
	v_add_co_u32_e32 v198, vcc, 0x200000, v196
	v_med3_i32 v15, v15, 0, v124
	s_nop 0
	v_addc_co_u32_e32 v199, vcc, 0, v197, vcc
	global_load_dword v118, v[196:197], off
	v_lshl_add_u32 v10, v10, 12, v14
	global_load_dword v120, v[120:121], off
	v_add_co_u32_e32 v196, vcc, 0x300000, v196
	v_lshl_add_u32 v14, v15, 12, v14
	s_nop 0
	v_addc_co_u32_e32 v197, vcc, 0, v197, vcc
	global_load_dwordx4 v[2:5], v2, s[52:53]
	s_nop 0
	global_load_dwordx4 v[6:9], v6, s[52:53]
	s_nop 0
	global_load_dwordx4 v[10:13], v10, s[52:53]
	s_nop 0
	global_load_dwordx4 v[14:17], v14, s[52:53]
	s_nop 0
	global_load_dword v121, v[198:199], off
	global_load_dword v119, v[196:197], off
.LBB0_672:
	ds_read_b128 v[196:199], v181
	ds_read_b128 v[200:203], v181 offset:64
	v_add_u32_e32 v195, s73, v180
	v_add_u32_e32 v210, s73, v179
	v_add_u32_e32 v211, s73, v178
	v_add_u32_e32 v212, s73, v163
	s_mov_b32 s26, 0xf149f2ca
	v_add_u32_e32 v213, s73, v162
	v_add_u32_e32 v214, s73, v160
	s_waitcnt lgkmcnt(1)
	v_mfma_f32_16x16x32_bf16 v[196:199], v[196:199], v[34:37], 0
	v_add_u32_e32 v216, s73, v159
	v_add_u32_e32 v150, 0x80, v150
	ds_read_b128 v[204:207], v183 offset:64
	s_waitcnt lgkmcnt(1)
	v_mfma_f32_16x16x32_bf16 v[196:199], v[200:203], v[38:41], v[196:199]
	ds_read_b128 v[200:203], v181 offset:128
	s_waitcnt lgkmcnt(0)
	v_mfma_f32_16x16x32_bf16 v[196:199], v[200:203], v[42:45], v[196:199]
	ds_read_b128 v[200:203], v181 offset:192
	s_waitcnt lgkmcnt(0)
	v_mfma_f32_16x16x32_bf16 v[196:199], v[200:203], v[46:49], v[196:199]
	ds_read_b128 v[200:203], v182
	s_nop 6
	v_mul_f32_e32 v114, v144, v196
	v_add_u32_e32 v196, 0x22800, v195
	ds_read_b32 v196, v196
	v_add_u32_e32 v195, 0x22880, v195
	ds_read_b32 v195, v195
	s_waitcnt lgkmcnt(1)
	v_fmac_f32_e32 v196, v200, v114
	v_cndmask_b32_e64 v114, v142, v196, s[10:11]
	v_mul_f32_e32 v196, v144, v197
	v_add_u32_e32 v197, 0x22800, v210
	ds_read_b32 v197, v197
	s_waitcnt lgkmcnt(0)
	v_fmac_f32_e32 v197, v201, v196
	v_cndmask_b32_e64 v196, v142, v197, s[12:13]
	v_mul_f32_e32 v197, v144, v198
	v_add_u32_e32 v198, 0x22800, v211
	ds_read_b32 v198, v198
	v_max3_f32 v200, v114, s26, v196
	s_waitcnt lgkmcnt(0)
	v_fmac_f32_e32 v198, v202, v197
	v_cndmask_b32_e64 v197, v142, v198, s[14:15]
	v_mul_f32_e32 v198, v144, v199
	v_add_u32_e32 v199, 0x22800, v212
	ds_read_b32 v199, v199
	s_waitcnt lgkmcnt(0)
	v_fmac_f32_e32 v199, v203, v198
	v_cndmask_b32_e64 v198, v142, v199, s[16:17]
	v_max3_f32 v208, v200, v197, v198
	ds_read_b128 v[200:203], v183
	s_waitcnt lgkmcnt(0)
	v_mfma_f32_16x16x32_bf16 v[200:203], v[200:203], v[34:37], 0
	v_mfma_f32_16x16x32_bf16 v[200:203], v[204:207], v[38:41], v[200:203]
	ds_read_b128 v[204:207], v183 offset:128
	s_waitcnt lgkmcnt(0)
	v_mfma_f32_16x16x32_bf16 v[200:203], v[204:207], v[42:45], v[200:203]
	ds_read_b128 v[204:207], v183 offset:192
	s_waitcnt lgkmcnt(0)
	v_mfma_f32_16x16x32_bf16 v[200:203], v[204:207], v[46:49], v[200:203]
	ds_read_b128 v[204:207], v184
	s_nop 6
	v_mul_f32_e32 v199, v144, v200
	v_add_u32_e32 v200, 0x22800, v213
	ds_read_b32 v200, v200
	v_mul_f32_e32 v202, v144, v202
	v_add_u32_e32 v213, 0x22880, v213
	ds_read_b32 v213, v213
	s_waitcnt lgkmcnt(1)
	v_fmac_f32_e32 v200, v204, v199
	v_cndmask_b32_e64 v199, v142, v200, s[18:19]
	v_mul_f32_e32 v200, v144, v201
	v_add_u32_e32 v201, s73, v161
	v_add_u32_e32 v204, 0x22800, v201
	ds_read_b32 v204, v204
	v_add_u32_e32 v201, 0x22880, v201
	ds_read_b32 v201, v201
	s_addk_i32 s73, 0x100
	s_cmp_lg_u32 s73, 0
	s_waitcnt lgkmcnt(1)
	v_fmac_f32_e32 v204, v205, v200
	v_add_u32_e32 v205, 0x22800, v214
	ds_read_b32 v205, v205
	v_cndmask_b32_e64 v200, v142, v204, s[20:21]
	v_max3_f32 v204, v208, v199, v200
	s_waitcnt lgkmcnt(0)
	v_fmac_f32_e32 v205, v206, v202
	v_mul_f32_e32 v202, v144, v203
	v_add_u32_e32 v203, 0x22800, v216
	ds_read_b32 v203, v203
	v_cndmask_b32_e64 v215, v142, v205, s[22:23]
	s_waitcnt lgkmcnt(0)
	v_fmac_f32_e32 v203, v207, v202
	v_cndmask_b32_e64 v217, v142, v203, s[24:25]
	v_max3_f32 v218, v204, v215, v217
	ds_read_b128 v[202:205], v185
	ds_read_b128 v[206:209], v185 offset:64
	s_waitcnt lgkmcnt(1)
	v_mfma_f32_16x16x32_bf16 v[202:205], v[202:205], v[34:37], 0
	s_waitcnt lgkmcnt(0)
	v_mfma_f32_16x16x32_bf16 v[202:205], v[206:209], v[38:41], v[202:205]
	ds_read_b128 v[206:209], v185 offset:128
	s_waitcnt lgkmcnt(0)
	v_mfma_f32_16x16x32_bf16 v[202:205], v[206:209], v[42:45], v[202:205]
	ds_read_b128 v[206:209], v185 offset:192
	s_waitcnt lgkmcnt(0)
	v_mfma_f32_16x16x32_bf16 v[202:205], v[206:209], v[46:49], v[202:205]
	ds_read_b128 v[206:209], v186
	s_nop 6
	v_mul_f32_e32 v202, v144, v202
	s_waitcnt lgkmcnt(0)
	v_fmac_f32_e32 v195, v206, v202
	v_add_u32_e32 v202, 0x22880, v210
	ds_read_b32 v202, v202
	v_cndmask_b32_e64 v219, v142, v195, s[10:11]
	v_mul_f32_e32 v195, v144, v203
	v_add_u32_e32 v203, 0x22880, v211
	ds_read_b32 v203, v203
	s_waitcnt lgkmcnt(1)
	v_fmac_f32_e32 v202, v207, v195
	v_cndmask_b32_e64 v210, v142, v202, s[12:13]
	v_mul_f32_e32 v202, v144, v204
	v_max3_f32 v195, v218, v219, v210
	s_waitcnt lgkmcnt(0)
	v_fmac_f32_e32 v203, v208, v202
	v_cndmask_b32_e64 v211, v142, v203, s[14:15]
	v_add_u32_e32 v203, 0x22880, v212
	ds_read_b32 v203, v203
	v_mul_f32_e32 v202, v144, v205
	s_waitcnt lgkmcnt(0)
	v_fmac_f32_e32 v203, v209, v202
	v_cndmask_b32_e64 v212, v142, v203, s[16:17]
	ds_read_b128 v[202:205], v187
	ds_read_b128 v[206:209], v187 offset:64
	s_waitcnt lgkmcnt(1)
	v_mfma_f32_16x16x32_bf16 v[202:205], v[202:205], v[34:37], 0
	v_max3_f32 v195, v195, v211, v212
	s_waitcnt lgkmcnt(0)
	v_mfma_f32_16x16x32_bf16 v[202:205], v[206:209], v[38:41], v[202:205]
	ds_read_b128 v[206:209], v187 offset:128
	s_waitcnt lgkmcnt(0)
	v_mfma_f32_16x16x32_bf16 v[202:205], v[206:209], v[42:45], v[202:205]
	ds_read_b128 v[206:209], v187 offset:192
	s_waitcnt lgkmcnt(0)
	v_mfma_f32_16x16x32_bf16 v[202:205], v[206:209], v[46:49], v[202:205]
	ds_read_b128 v[206:209], v188
	s_nop 6
	v_mul_f32_e32 v203, v144, v203
	v_mul_f32_e32 v202, v144, v202
	s_waitcnt lgkmcnt(0)
	v_fmac_f32_e32 v201, v207, v203
	v_mul_f32_e32 v203, v144, v204
	v_add_u32_e32 v204, 0x22880, v214
	ds_read_b32 v204, v204
	v_fmac_f32_e32 v213, v206, v202
	v_cndmask_b32_e64 v202, v142, v213, s[18:19]
	v_cndmask_b32_e64 v201, v142, v201, s[20:21]
	v_max3_f32 v195, v195, v202, v201
	s_waitcnt lgkmcnt(0)
	v_fmac_f32_e32 v204, v208, v203
	v_cndmask_b32_e64 v203, v142, v204, s[22:23]
	v_mul_f32_e32 v204, v144, v205
	v_add_u32_e32 v205, 0x22880, v216
	ds_read_b32 v205, v205
	s_waitcnt lgkmcnt(0)
	v_fmac_f32_e32 v205, v209, v204
	v_cndmask_b32_e64 v204, v142, v205, s[24:25]
	v_max3_f32 v195, v195, v203, v204
	ds_bpermute_b32 v205, v131, v195
	s_waitcnt lgkmcnt(0)
	v_max_f32_e32 v205, v205, v205
	v_max_f32_e32 v195, v195, v205
	ds_bpermute_b32 v205, v132, v195
	s_waitcnt lgkmcnt(0)
	v_max3_f32 v195, v194, v195, v205
	v_sub_f32_e32 v114, v114, v195
	v_exp_f32_e32 v213, v114
	v_sub_f32_e32 v196, v196, v195
	v_exp_f32_e32 v214, v196
	v_sub_f32_e32 v196, v197, v195
	v_exp_f32_e32 v197, v196
	v_sub_f32_e32 v196, v198, v195
	v_exp_f32_e32 v216, v196
	v_sub_f32_e32 v196, v199, v195
	v_add_f32_e32 v114, 0, v213
	v_exp_f32_e32 v218, v196
	v_sub_f32_e32 v196, v200, v195
	v_add_f32_e32 v114, v214, v114
	v_exp_f32_e32 v220, v196
	v_sub_f32_e32 v196, v215, v195
	v_add_f32_e32 v114, v197, v114
	v_exp_f32_e32 v215, v196
	v_sub_f32_e32 v196, v217, v195
	v_add_f32_e32 v114, v216, v114
	v_exp_f32_e32 v217, v196
	v_sub_f32_e32 v196, v219, v195
	v_add_f32_e32 v114, v218, v114
	v_exp_f32_e32 v219, v196
	v_sub_f32_e32 v196, v210, v195
	v_add_f32_e32 v114, v220, v114
	v_exp_f32_e32 v210, v196
	v_sub_f32_e32 v196, v211, v195
	v_add_f32_e32 v114, v215, v114
	v_exp_f32_e32 v211, v196
	v_sub_f32_e32 v196, v212, v195
	v_add_f32_e32 v114, v217, v114
	v_exp_f32_e32 v212, v196
	v_sub_f32_e32 v196, v202, v195
	v_add_f32_e32 v114, v219, v114
	v_exp_f32_e32 v221, v196
	v_sub_f32_e32 v196, v201, v195
	v_add_f32_e32 v114, v210, v114
	v_exp_f32_e32 v222, v196
	v_sub_f32_e32 v196, v203, v195
	v_add_f32_e32 v114, v211, v114
	v_exp_f32_e32 v223, v196
	v_sub_f32_e32 v196, v204, v195
	v_add_f32_e32 v114, v212, v114
	v_exp_f32_e32 v224, v196
	v_add_f32_e32 v114, v221, v114
	v_add_f32_e32 v114, v222, v114
	v_sub_f32_e32 v194, v194, v195
	v_add_f32_e32 v114, v223, v114
	v_add_f32_e32 v196, v224, v114
	v_exp_f32_e32 v114, v194
	ds_bpermute_b32 v194, v131, v196
	v_pk_mul_f32 v[206:207], v[54:55], v[114:115] op_sel_hi:[1,0]
	v_pk_mul_f32 v[54:55], v[70:71], v[114:115] op_sel_hi:[1,0]
	v_add_u32_e32 v70, v174, v177
	v_pk_mul_f32 v[200:201], v[60:61], v[114:115] op_sel_hi:[1,0]
	v_pk_mul_f32 v[198:199], v[58:59], v[114:115] op_sel_hi:[1,0]
	v_pk_mul_f32 v[204:205], v[52:53], v[114:115] op_sel_hi:[1,0]
	v_pk_mul_f32 v[202:203], v[50:51], v[114:115] op_sel_hi:[1,0]
	v_pk_mul_f32 v[60:61], v[76:77], v[114:115] op_sel_hi:[1,0]
	v_pk_mul_f32 v[58:59], v[74:75], v[114:115] op_sel_hi:[1,0]
	v_pk_mul_f32 v[52:53], v[80:81], v[114:115] op_sel_hi:[1,0]
	v_pk_mul_f32 v[50:51], v[78:79], v[114:115] op_sel_hi:[1,0]
	s_mov_b64 vcc, s[98:99]
	s_cbranch_vccz .Lmy_na_vw_all
	s_waitcnt vmcnt(12)
	s_branch .Lmy_na_vw_done

.Lmy_na_vw_done:
	ds_write_b128 v70, v[82:85]
	ds_write_b128 v70, v[86:89] offset:8704
	ds_write_b128 v70, v[90:93] offset:17408
	ds_write_b128 v70, v[94:97] offset:26112
	ds_write_b128 v70, v[98:101] offset:34816
	ds_write_b128 v70, v[102:105] offset:43520
	ds_write_b128 v70, v[106:109] offset:52224
	ds_write_b128 v70, v[110:113] offset:60928
	s_waitcnt lgkmcnt(0)
	s_barrier
	ds_read_b64_tr_b16 v[76:77], v190
	ds_read_b64_tr_b16 v[80:81], v190 offset:32
	ds_read_b64_tr_b16 v[74:75], v189
	ds_read_b64_tr_b16 v[78:79], v189 offset:32
	ds_read_b64_tr_b16 v[82:83], v189 offset:64
	ds_read_b64_tr_b16 v[84:85], v190 offset:64
	ds_read_b64_tr_b16 v[86:87], v189 offset:96
	ds_read_b64_tr_b16 v[88:89], v190 offset:96
	v_pk_mul_f32 v[208:209], v[56:57], v[114:115] op_sel_hi:[1,0]
	v_pk_mul_f32 v[64:65], v[64:65], v[114:115] op_sel_hi:[1,0]
	v_pk_mul_f32 v[62:63], v[62:63], v[114:115] op_sel_hi:[1,0]
	v_pk_mul_f32 v[56:57], v[72:73], v[114:115] op_sel_hi:[1,0]
	v_cvt_pk_bf16_f32 v70, v213, v214
	v_cvt_pk_bf16_f32 v71, v197, v216
	v_cvt_pk_bf16_f32 v72, v218, v220
	v_cvt_pk_bf16_f32 v73, v215, v217
	v_pk_mul_f32 v[68:69], v[68:69], v[114:115] op_sel_hi:[1,0]
	v_pk_mul_f32 v[66:67], v[66:67], v[114:115] op_sel_hi:[1,0]
	s_waitcnt lgkmcnt(0)
	v_mfma_f32_16x16x32_bf16 v[62:65], v[86:89], v[70:73], v[62:65]
	ds_read_b64_tr_b16 v[86:87], v189 offset:128
	ds_read_b64_tr_b16 v[88:89], v190 offset:128
	v_cvt_pk_bf16_f32 v98, v219, v210
	v_cvt_pk_bf16_f32 v99, v211, v212
	s_waitcnt lgkmcnt(0)
	v_mfma_f32_16x16x32_bf16 v[66:69], v[86:89], v[70:73], v[66:69]
	ds_read_b64_tr_b16 v[86:87], v189 offset:160
	ds_read_b64_tr_b16 v[88:89], v190 offset:160
	v_cvt_pk_bf16_f32 v100, v221, v222
	v_cvt_pk_bf16_f32 v101, v223, v224
	s_waitcnt lgkmcnt(0)
	v_mfma_f32_16x16x32_bf16 v[86:89], v[86:89], v[70:73], v[58:61]
	s_nop 2
	ds_read_b64_tr_b16 v[58:59], v189 offset:192
	ds_read_b64_tr_b16 v[60:61], v190 offset:192
	v_add_f32_e32 v194, v196, v194
	ds_bpermute_b32 v196, v132, v194
	s_waitcnt lgkmcnt(1)
	v_mfma_f32_16x16x32_bf16 v[90:93], v[58:61], v[70:73], v[54:57]
	s_nop 2
	ds_read_b64_tr_b16 v[54:55], v189 offset:224
	ds_read_b64_tr_b16 v[56:57], v190 offset:224
	s_waitcnt lgkmcnt(2)
	v_add_f32_e32 v196, v194, v196
	v_fmac_f32_e32 v196, v193, v114
	s_waitcnt lgkmcnt(0)
	v_mfma_f32_16x16x32_bf16 v[94:97], v[54:57], v[70:73], v[50:53]
	s_nop 2
	ds_read_b64_tr_b16 v[52:53], v192
	ds_read_b64_tr_b16 v[56:57], v192 offset:32
	ds_read_b64_tr_b16 v[50:51], v191
	ds_read_b64_tr_b16 v[54:55], v191 offset:32
	v_mfma_f32_16x16x32_bf16 v[74:77], v[74:77], v[70:73], v[198:201]
	v_mfma_f32_16x16x32_bf16 v[78:81], v[78:81], v[70:73], v[202:205]
	v_mfma_f32_16x16x32_bf16 v[82:85], v[82:85], v[70:73], v[206:209]
	s_waitcnt lgkmcnt(1)
	v_mfma_f32_16x16x32_bf16 v[58:61], v[50:53], v[98:101], v[74:77]
	s_waitcnt lgkmcnt(0)
	v_mfma_f32_16x16x32_bf16 v[50:53], v[54:57], v[98:101], v[78:81]
	ds_read_b64_tr_b16 v[54:55], v191 offset:64
	ds_read_b64_tr_b16 v[56:57], v192 offset:64
	ds_read_b64_tr_b16 v[70:71], v191 offset:96
	ds_read_b64_tr_b16 v[72:73], v192 offset:96
	s_waitcnt lgkmcnt(0)
	v_mfma_f32_16x16x32_bf16 v[62:65], v[70:73], v[98:101], v[62:65]
	ds_read_b64_tr_b16 v[70:71], v191 offset:128
	ds_read_b64_tr_b16 v[72:73], v192 offset:128
	s_waitcnt lgkmcnt(0)
	v_mfma_f32_16x16x32_bf16 v[66:69], v[70:73], v[98:101], v[66:69]
	ds_read_b64_tr_b16 v[70:71], v191 offset:160
	ds_read_b64_tr_b16 v[72:73], v192 offset:160
	s_waitcnt lgkmcnt(0)
	v_mfma_f32_16x16x32_bf16 v[74:77], v[70:73], v[98:101], v[86:89]
	ds_read_b64_tr_b16 v[70:71], v191 offset:192
	ds_read_b64_tr_b16 v[72:73], v192 offset:192
	ds_read_b64_tr_b16 v[78:79], v191 offset:224
	ds_read_b64_tr_b16 v[80:81], v192 offset:224
	v_mfma_f32_16x16x32_bf16 v[54:57], v[54:57], v[98:101], v[82:85]
	s_waitcnt lgkmcnt(2)
	v_mfma_f32_16x16x32_bf16 v[70:73], v[70:73], v[98:101], v[90:93]
	s_waitcnt lgkmcnt(0)
	v_mfma_f32_16x16x32_bf16 v[78:81], v[78:81], v[98:101], v[94:97]
	s_cbranch_scc0 .LBB0_637
	v_mov_b32_e32 v194, v195
	v_mov_b32_e32 v193, v196
	s_branch .LBB0_661
